# scan: o stores in scalar-base form (ws base + 32-bit lane offset), one add per store instead of a 64-bit add pair
# speedup vs baseline: 1.0003x; 1.0003x over previous
.LBB0_161:
	s_andn2_b64 vcc, exec, s[6:7]
	s_cbranch_vccnz .LBB0_158
	s_mul_i32 s11, s11, 0x12000
	s_add_i32 s6, s11, 0
	v_add_u32_e32 v0, s6, v58
	v_add_u32_e32 v2, s6, v59
	v_add_u32_e32 v3, s6, v60
	v_add_u32_e32 v142, s6, v61
	ds_read_b128 v[62:65], v0
	ds_read_b128 v[66:69], v0 offset:4096
	ds_read_b128 v[70:73], v2
	ds_read_b128 v[74:77], v2 offset:4096
	ds_read_b128 v[78:81], v3
	ds_read_b128 v[82:85], v3 offset:4096
	ds_read_b128 v[86:89], v142
	ds_read_b128 v[90:93], v142 offset:4096
	ds_read_b128 v[94:97], v0 offset:8192
	ds_read_b128 v[98:101], v0 offset:12288
	ds_read_b128 v[102:105], v2 offset:8192
	ds_read_b128 v[106:109], v2 offset:12288
	ds_read_b128 v[110:113], v3 offset:8192
	ds_read_b128 v[114:117], v3 offset:12288
	ds_read_b128 v[118:121], v142 offset:8192
	ds_read_b128 v[122:125], v142 offset:12288
	ds_read_b128 v[126:129], v0 offset:16384
	ds_read_b128 v[130:133], v0 offset:20480
	ds_read_b128 v[134:137], v2 offset:16384
	ds_read_b128 v[138:141], v2 offset:20480
	ds_read_b128 v[146:149], v3 offset:16384
	ds_read_b128 v[154:157], v3 offset:20480
	ds_read_b128 v[162:165], v142 offset:16384
	ds_read_b128 v[166:169], v142 offset:20480
	ds_read_b128 v[170:173], v0 offset:24576
	ds_read_b128 v[174:177], v0 offset:28672
	ds_read_b128 v[178:181], v2 offset:24576
	ds_read_b128 v[182:185], v2 offset:28672
	ds_read_b128 v[186:189], v3 offset:24576
	ds_read_b128 v[190:193], v3 offset:28672
	ds_read_b128 v[194:197], v142 offset:24576
	ds_read_b128 v[198:201], v142 offset:28672
	v_cvt_pk_bf16_f32 v202, v12, v13
	v_cvt_pk_bf16_f32 v203, v14, v15
	v_cvt_pk_bf16_f32 v204, v4, v5
	v_cvt_pk_bf16_f32 v205, v6, v7
	v_cvt_pk_bf16_f32 v206, v8, v9
	v_cvt_pk_bf16_f32 v207, v10, v11
	v_cvt_pk_bf16_f32 v208, v16, v17
	v_cvt_pk_bf16_f32 v209, v18, v19
	v_cvt_pk_bf16_f32 v210, v20, v21
	v_cvt_pk_bf16_f32 v211, v22, v23
	v_cvt_pk_bf16_f32 v212, v24, v25
	v_cvt_pk_bf16_f32 v213, v26, v27
	v_cvt_pk_bf16_f32 v222, v28, v29
	v_cvt_pk_bf16_f32 v223, v30, v31
	v_cvt_pk_bf16_f32 v224, v32, v33
	v_cvt_pk_bf16_f32 v225, v34, v35
	s_waitcnt lgkmcnt(14)
	v_mfma_f32_16x16x32_bf16 v[62:65], v[62:65], v[202:205], 0
	v_add3_u32 v0, s6, v56, v57
	v_add_u32_e32 v145, s6, v55
	v_add_u32_e32 v159, s6, v54
	v_mfma_f32_16x16x32_bf16 v[66:69], v[66:69], v[202:205], 0
	ds_read2st64_b32 v[2:3], v0 offset0:224 offset1:225
	ds_read2st64_b32 v[142:143], v0 offset0:226 offset1:227
	v_mfma_f32_16x16x32_bf16 v[62:65], v[70:73], v[206:209], v[62:65]
	v_mfma_f32_16x16x32_bf16 v[66:69], v[74:77], v[206:209], v[66:69]
	v_mfma_f32_16x16x32_bf16 v[70:73], v[94:97], v[202:205], 0
	v_mfma_f32_16x16x32_bf16 v[62:65], v[78:81], v[210:213], v[62:65]
	ds_read_b128 v[78:81], v145 offset:49152
	v_mfma_f32_16x16x32_bf16 v[66:69], v[82:85], v[210:213], v[66:69]
	v_mfma_f32_16x16x32_bf16 v[74:77], v[98:101], v[202:205], 0
	v_mfma_f32_16x16x32_bf16 v[70:73], v[102:105], v[206:209], v[70:73]
	v_add_u32_e32 v102, 0xe000, v0
	v_mfma_f32_16x16x32_bf16 v[62:65], v[86:89], v[222:225], v[62:65]
	v_mfma_f32_16x16x32_bf16 v[66:69], v[90:93], v[222:225], v[66:69]
	v_mfma_f32_16x16x32_bf16 v[74:77], v[106:109], v[206:209], v[74:77]
	ds_read_b128 v[82:85], v159 offset:49152
	ds_read2st64_b32 v[226:227], v0 offset0:240 offset1:241
	ds_read2st64_b32 v[228:229], v0 offset0:242 offset1:243
	ds_read_b128 v[86:89], v145 offset:51200
	ds_read_b128 v[90:93], v159 offset:51200
	ds_read2st64_b32 v[230:231], v102 offset0:32 offset1:33
	ds_read2st64_b32 v[232:233], v102 offset0:34 offset1:35
	ds_read_b128 v[94:97], v145 offset:53248
	ds_read_b128 v[98:101], v159 offset:53248
	ds_read2st64_b32 v[234:235], v102 offset0:48 offset1:49
	ds_read2st64_b32 v[236:237], v102 offset0:50 offset1:51
	ds_read_b128 v[102:105], v145 offset:55296
	ds_read_b128 v[106:109], v159 offset:55296
	v_mfma_f32_16x16x32_bf16 v[70:73], v[110:113], v[210:213], v[70:73]
	v_mfma_f32_16x16x32_bf16 v[74:77], v[114:117], v[210:213], v[74:77]
	v_mfma_f32_16x16x32_bf16 v[70:73], v[118:121], v[222:225], v[70:73]
	v_mfma_f32_16x16x32_bf16 v[74:77], v[122:125], v[222:225], v[74:77]
	v_mfma_f32_16x16x32_bf16 v[110:113], v[126:129], v[202:205], 0
	v_mfma_f32_16x16x32_bf16 v[114:117], v[130:133], v[202:205], 0
	s_waitcnt lgkmcnt(14)
	v_mfma_f32_16x16x32_bf16 v[118:121], v[170:173], v[202:205], 0
	v_mfma_f32_16x16x32_bf16 v[122:125], v[174:177], v[202:205], 0
	v_mfma_f32_16x16x32_bf16 v[110:113], v[134:137], v[206:209], v[110:113]
	v_mfma_f32_16x16x32_bf16 v[114:117], v[138:141], v[206:209], v[114:117]
	v_mfma_f32_16x16x32_bf16 v[118:121], v[178:181], v[206:209], v[118:121]
	v_mfma_f32_16x16x32_bf16 v[122:125], v[182:185], v[206:209], v[122:125]
	v_mfma_f32_16x16x32_bf16 v[110:113], v[146:149], v[210:213], v[110:113]
	v_mfma_f32_16x16x32_bf16 v[114:117], v[154:157], v[210:213], v[114:117]
	v_mfma_f32_16x16x32_bf16 v[118:121], v[186:189], v[210:213], v[118:121]
	v_mfma_f32_16x16x32_bf16 v[122:125], v[190:193], v[210:213], v[122:125]
	v_mfma_f32_16x16x32_bf16 v[110:113], v[162:165], v[222:225], v[110:113]
	v_mfma_f32_16x16x32_bf16 v[114:117], v[166:169], v[222:225], v[114:117]
	v_mfma_f32_16x16x32_bf16 v[118:121], v[194:197], v[222:225], v[118:121]
	v_mfma_f32_16x16x32_bf16 v[122:125], v[198:201], v[222:225], v[122:125]
	ds_read_b128 v[126:129], v145 offset:32768
	ds_read_b128 v[130:133], v159 offset:32768
	ds_read_b128 v[134:137], v145 offset:34816
	ds_read_b128 v[138:141], v159 offset:34816
	ds_read_b128 v[146:149], v145 offset:36864
	ds_read_b128 v[154:157], v159 offset:36864
	ds_read_b128 v[162:165], v145 offset:38912
	ds_read_b128 v[166:169], v159 offset:38912
	ds_read_b128 v[170:173], v145 offset:40960
	ds_read_b128 v[174:177], v159 offset:40960
	ds_read_b128 v[178:181], v145 offset:43008
	ds_read_b128 v[182:185], v159 offset:43008
	ds_read_b128 v[186:189], v145 offset:45056
	ds_read_b128 v[190:193], v159 offset:45056
	ds_read_b128 v[194:197], v145 offset:47104
	ds_read_b128 v[198:201], v159 offset:47104
	v_pk_add_f32 v[2:3], v[2:3], v[62:63] neg_lo:[0,1] neg_hi:[0,1]
	v_pk_add_f32 v[64:65], v[142:143], v[64:65] neg_lo:[0,1] neg_hi:[0,1]
	s_waitcnt lgkmcnt(14)
	v_pk_add_f32 v[66:67], v[226:227], v[66:67] neg_lo:[0,1] neg_hi:[0,1]
	v_pk_add_f32 v[68:69], v[228:229], v[68:69] neg_lo:[0,1] neg_hi:[0,1]
	v_pk_add_f32 v[70:71], v[230:231], v[70:71] neg_lo:[0,1] neg_hi:[0,1]
	v_cvt_pk_bf16_f32 v62, v2, v3
	v_cvt_pk_bf16_f32 v63, v64, v65
	v_cvt_pk_bf16_f32 v64, v66, v67
	v_cvt_pk_bf16_f32 v65, v68, v69
	v_pk_add_f32 v[142:143], v[232:233], v[72:73] neg_lo:[0,1] neg_hi:[0,1]
	v_cvt_pk_bf16_f32 v66, v70, v71
	v_mfma_f32_16x16x32_bf16 v[70:73], v[78:81], v[62:65], v[110:113]
	v_readlane_b32 s6, v37, s10
	v_pk_add_f32 v[74:75], v[234:235], v[74:75] neg_lo:[0,1] neg_hi:[0,1]
	v_pk_add_f32 v[76:77], v[236:237], v[76:77] neg_lo:[0,1] neg_hi:[0,1]
	v_pk_mul_f32 v[6:7], v[6:7], s[6:7] op_sel_hi:[1,0]
	v_pk_mul_f32 v[4:5], v[4:5], s[6:7] op_sel_hi:[1,0]
	v_cvt_pk_bf16_f32 v67, v142, v143
	v_cvt_pk_bf16_f32 v68, v74, v75
	v_cvt_pk_bf16_f32 v69, v76, v77
	s_waitcnt lgkmcnt(13)
	v_mfma_f32_16x16x32_bf16 v[2:5], v[134:137], v[62:65], v[4:7]
	v_mul_f32_e64 v14, v14, s6
	v_mul_f32_e64 v15, v15, s6
	v_pk_mul_f32 v[12:13], v[12:13], s[6:7] op_sel_hi:[1,0]
	v_pk_mul_f32 v[10:11], v[10:11], s[6:7] op_sel_hi:[1,0]
	v_mfma_f32_16x16x32_bf16 v[70:73], v[82:85], v[66:69], v[70:73]
	v_mul_f32_e64 v8, v8, s6
	v_mul_f32_e64 v9, v9, s6
	v_pk_mul_f32 v[18:19], v[18:19], s[6:7] op_sel_hi:[1,0]
	v_pk_mul_f32 v[16:17], v[16:17], s[6:7] op_sel_hi:[1,0]
	v_mfma_f32_16x16x32_bf16 v[74:77], v[86:89], v[62:65], v[114:117]
	v_mul_f32_e64 v22, v22, s6
	v_mul_f32_e64 v23, v23, s6
	s_nop 0
	v_cvt_pk_bf16_f32 v0, v70, s0
	v_pk_mul_f32 v[20:21], v[20:21], s[6:7] op_sel_hi:[1,0]
	s_waitcnt lgkmcnt(12)
	v_mfma_f32_16x16x32_bf16 v[4:7], v[138:141], v[66:69], v[2:5]
	v_mul_f32_e64 v26, v26, s6
	v_mul_f32_e64 v27, v27, s6
	v_pk_mul_f32 v[24:25], v[24:25], s[6:7] op_sel_hi:[1,0]
	v_pk_mul_f32 v[30:31], v[30:31], s[6:7] op_sel_hi:[1,0]
	v_add_u32_e32 v70, 0x1000, v38
	v_pk_mul_f32 v[28:29], v[28:29], s[6:7] op_sel_hi:[1,0]
	v_pk_mul_f32 v[34:35], v[34:35], s[6:7] op_sel_hi:[1,0]
	v_pk_mul_f32 v[32:33], v[32:33], s[6:7] op_sel_hi:[1,0]
	global_store_short v38, v0, s[2:3]
	v_cvt_pk_bf16_f32 v0, v71, s0
	global_store_short v70, v0, s[2:3] offset:2048
	v_add_u32_e32 v70, 0x3000, v38
	v_mfma_f32_16x16x32_bf16 v[74:77], v[90:93], v[66:69], v[74:77]
	v_cvt_pk_bf16_f32 v0, v72, s0
	global_store_short v70, v0, s[2:3]
	v_add_u32_e32 v70, 0x4000, v38
	v_cvt_pk_bf16_f32 v0, v73, s0
	global_store_short v70, v0, s[2:3] offset:2048
	v_add_u32_e32 v70, 0x18000, v38
	v_mfma_f32_16x16x32_bf16 v[78:81], v[94:97], v[62:65], v[118:121]
	v_cvt_pk_bf16_f32 v0, v74, s0
	global_store_short v70, v0, s[2:3]
	v_add_u32_e32 v70, 0x19000, v38
	v_mfma_f32_16x16x32_bf16 v[82:85], v[102:105], v[62:65], v[122:125]
	v_cvt_pk_bf16_f32 v0, v75, s0
	global_store_short v70, v0, s[2:3] offset:2048
	v_cvt_pk_bf16_f32 v0, v76, s0
	v_mfma_f32_16x16x32_bf16 v[12:15], v[126:129], v[62:65], v[12:15]
	s_waitcnt lgkmcnt(11)
	v_mfma_f32_16x16x32_bf16 v[8:11], v[146:149], v[62:65], v[8:11]
	s_waitcnt lgkmcnt(9)
	v_mfma_f32_16x16x32_bf16 v[16:19], v[162:165], v[62:65], v[16:19]
	s_waitcnt lgkmcnt(7)
	v_mfma_f32_16x16x32_bf16 v[20:23], v[170:173], v[62:65], v[20:23]
	s_waitcnt lgkmcnt(5)
	v_mfma_f32_16x16x32_bf16 v[24:27], v[178:181], v[62:65], v[24:27]
	s_waitcnt lgkmcnt(3)
	v_mfma_f32_16x16x32_bf16 v[28:31], v[186:189], v[62:65], v[28:31]
	s_waitcnt lgkmcnt(1)
	v_mfma_f32_16x16x32_bf16 v[32:35], v[194:197], v[62:65], v[32:35]
	v_add_u32_e32 v62, 0x1b000, v38
	v_mfma_f32_16x16x32_bf16 v[78:81], v[98:101], v[66:69], v[78:81]
	global_store_short v62, v0, s[2:3]
	v_add_u32_e32 v62, 0x1c000, v38
	v_cvt_pk_bf16_f32 v0, v77, s0
	global_store_short v62, v0, s[2:3] offset:2048
	v_add_u32_e32 v62, 0x30000, v38
	v_cvt_pk_bf16_f32 v0, v78, s0
	global_store_short v62, v0, s[2:3]
	v_add_u32_e32 v62, 0x31000, v38
	v_cvt_pk_bf16_f32 v0, v79, s0
	global_store_short v62, v0, s[2:3] offset:2048
	v_add_u32_e32 v62, 0x33000, v38
	v_mfma_f32_16x16x32_bf16 v[82:85], v[106:109], v[66:69], v[82:85]
	v_cvt_pk_bf16_f32 v0, v80, s0
	global_store_short v62, v0, s[2:3]
	v_add_u32_e32 v62, 0x34000, v38
	v_cvt_pk_bf16_f32 v0, v81, s0
	global_store_short v62, v0, s[2:3] offset:2048
	v_add_u32_e32 v62, 0x48000, v38
	v_cvt_pk_bf16_f32 v0, v82, s0
	global_store_short v62, v0, s[2:3]
	v_add_u32_e32 v62, 0x49000, v38
	v_cvt_pk_bf16_f32 v0, v83, s0
	global_store_short v62, v0, s[2:3] offset:2048
	v_add_u32_e32 v62, 0x4b000, v38
	v_cvt_pk_bf16_f32 v0, v84, s0
	v_add_u32_e32 v2, 0x4c000, v38
	global_store_short v62, v0, s[2:3]
	v_cvt_pk_bf16_f32 v0, v85, s0
	v_mfma_f32_16x16x32_bf16 v[12:15], v[130:133], v[66:69], v[12:15]
	global_store_short v2, v0, s[2:3] offset:2048
	s_waitcnt vmcnt(16) lgkmcnt(0)
	s_barrier
	v_mfma_f32_16x16x32_bf16 v[8:11], v[154:157], v[66:69], v[8:11]
	v_mfma_f32_16x16x32_bf16 v[16:19], v[166:169], v[66:69], v[16:19]
	v_mfma_f32_16x16x32_bf16 v[20:23], v[174:177], v[66:69], v[20:23]
	v_mfma_f32_16x16x32_bf16 v[24:27], v[182:185], v[66:69], v[24:27]
	v_mfma_f32_16x16x32_bf16 v[28:31], v[190:193], v[66:69], v[28:31]
	s_waitcnt lgkmcnt(0)
	v_mfma_f32_16x16x32_bf16 v[32:35], v[198:201], v[66:69], v[32:35]
	s_branch .LBB0_158
